# phase-3 work queue: first item of every block assigned statically (item = blockIdx.x, no atomic), later claims = gridDim + atomic; removes the 256-way contended first claim from the critical DeltaNet
# speedup vs baseline: 1.0026x; 1.0026x over previous
.LBB0_620:
	v_writelane_b32 v255, s46, 51
	s_waitcnt vmcnt(0)
	v_and_b32_e32 v0, 63, v224
	v_lshlrev_b32_e32 v0, 2, v0
	v_writelane_b32 v255, s47, 52
	v_mbcnt_lo_u32_b32 v5, -1, 0
	v_readlane_b32 s0, v255, 6
	v_readlane_b32 s1, v255, 7
	v_readlane_b32 s2, v255, 8
	v_readlane_b32 s3, v255, 9
	v_readlane_b32 s4, v255, 10
	v_readlane_b32 s5, v255, 11
	v_readlane_b32 s6, v255, 12
	v_readlane_b32 s7, v255, 13
	v_readlane_b32 s8, v255, 14
	v_readlane_b32 s9, v255, 15
	v_readlane_b32 s10, v255, 16
	v_readlane_b32 s11, v255, 17
	v_readlane_b32 s12, v255, 18
	v_readlane_b32 s13, v255, 19
	v_readlane_b32 s14, v255, 20
	v_readlane_b32 s15, v255, 21
	s_nop 0
	global_load_dword v1, v0, s[10:11]
	s_nop 0
	global_load_dword v3, v0, s[12:13]
	s_nop 0
	global_load_dword v4, v0, s[14:15]
	v_readlane_b32 s0, v255, 22
	v_readlane_b32 s1, v255, 23
	v_mbcnt_hi_u32_b32 v5, -1, v5
	v_and_b32_e32 v6, 64, v5
	v_xor_b32_e32 v7, 32, v5
	v_add_u32_e32 v6, 64, v6
	v_xor_b32_e32 v8, 16, v5
	global_load_dword v0, v0, s[0:1]
	v_cmp_lt_i32_e32 vcc, v7, v6
	v_xor_b32_e32 v9, 8, v5
	v_xor_b32_e32 v10, 4, v5
	v_cndmask_b32_e32 v7, v5, v7, vcc
	v_cmp_lt_i32_e32 vcc, v8, v6
	v_xor_b32_e32 v11, 2, v5
	v_xor_b32_e32 v12, 1, v5
	v_cndmask_b32_e32 v8, v5, v8, vcc
	v_cmp_lt_i32_e32 vcc, v9, v6
	v_lshlrev_b32_e32 v148, 2, v7
	v_lshlrev_b32_e32 v149, 2, v8
	v_cndmask_b32_e32 v9, v5, v9, vcc
	v_cmp_lt_i32_e32 vcc, v10, v6
	v_lshlrev_b32_e32 v8, 2, v9
	s_add_u32 s0, s28, 0x163fc000
	v_cndmask_b32_e32 v10, v5, v10, vcc
	v_cmp_lt_i32_e32 vcc, v11, v6
	v_lshlrev_b32_e32 v9, 2, v10
	s_addc_u32 s1, s29, 0
	v_cndmask_b32_e32 v11, v5, v11, vcc
	v_cmp_lt_i32_e32 vcc, v12, v6
	s_add_u32 s16, s28, 0x8700000
	s_addc_u32 s17, s29, 0
	v_cndmask_b32_e32 v5, v5, v12, vcc
	s_add_u32 s58, s28, 0x15f00000
	s_addc_u32 s59, s29, 0
	s_add_u32 s64, s28, 0x1600000
	s_addc_u32 s65, s29, 0
	s_waitcnt lgkmcnt(0)
	s_add_u32 s74, s28, 0xfb00000
	v_readlane_b32 s2, v255, 24
	v_readlane_b32 s3, v255, 25
	v_readlane_b32 s4, v255, 26
	v_readlane_b32 s5, v255, 27
	v_readlane_b32 s6, v255, 28
	v_readlane_b32 s7, v255, 29
	v_readlane_b32 s8, v255, 30
	v_readlane_b32 s9, v255, 31
	v_readlane_b32 s10, v255, 32
	v_readlane_b32 s11, v255, 33
	v_readlane_b32 s12, v255, 34
	v_readlane_b32 s13, v255, 35
	v_readlane_b32 s14, v255, 36
	v_readlane_b32 s15, v255, 37
	v_writelane_b32 v255, s0, 49
	s_addc_u32 s75, s29, 0
	s_mov_b64 s[40:41], src_shared_base
	v_writelane_b32 v255, s1, 50
	s_add_u32 s0, s28, 0x10d00000
	s_addc_u32 s1, s29, 0
	v_writelane_b32 v255, s0, 53
	s_mov_b64 s[48:49], 0
	s_mov_b64 s[46:47], 0
	v_writelane_b32 v255, s1, 54
	s_add_u32 s0, s28, 0x11500000
	s_addc_u32 s1, s29, 0
	s_add_u32 s44, s28, 0x6700000
	s_addc_u32 s45, s29, 0
	v_writelane_b32 v255, s0, 55
	s_add_u32 s72, s28, 0xfb20000
	v_mov_b32_e32 v2, 0
	s_movk_i32 s20, 0x3a00
	s_mov_b64 s[50:51], 0x800
	s_movk_i32 s21, 0x110
	s_movk_i32 s22, 0x210
	s_movk_i32 s23, 0x48
	s_movk_i32 s24, 0x90
	s_movk_i32 s25, 0x840
	s_mov_b64 s[52:53], 0x80
	s_mov_b32 s26, 0xf149f2ca
	s_mov_b32 s27, 0x3e38aa3b
	s_waitcnt vmcnt(2)
	v_mul_f32_e32 v6, v1, v3
	ds_bpermute_b32 v6, v148, v6
	v_mov_b32_e32 v137, 0x358637bd
	v_mov_b32_e32 v225, 0xffffd000
	v_mov_b32_e32 v254, 0x13f00000
	v_mov_b32_e32 v144, 0x11f00000
	s_waitcnt lgkmcnt(0)
	v_fmac_f32_e32 v6, v1, v3
	v_lshlrev_b32_e32 v3, 2, v11
	v_mov_b32_e32 v145, 0xffffff80
	s_waitcnt vmcnt(0)
	v_mul_f32_e32 v7, v4, v0
	ds_bpermute_b32 v7, v148, v7
	v_mov_b32_e32 v146, 0x900
	v_mov_b32_e32 v147, 0x1200
	v_writelane_b32 v255, s1, 56
	s_addc_u32 s73, s29, 0
	s_waitcnt lgkmcnt(0)
	v_fmac_f32_e32 v7, v4, v0
	ds_bpermute_b32 v0, v149, v6
	ds_bpermute_b32 v1, v149, v7
	v_lshlrev_b32_e32 v4, 2, v5
	s_add_i32 s40, 16, 0x18800
	s_add_i32 s54, 16, 0x1cc00
	s_waitcnt lgkmcnt(1)
	v_add_f32_e32 v0, v6, v0
	s_waitcnt lgkmcnt(0)
	v_add_f32_e32 v1, v7, v1
	ds_bpermute_b32 v5, v8, v0
	ds_bpermute_b32 v6, v8, v1
	s_add_i32 s55, 16, 0x25800
	v_mov_b32_e32 v151, 0x1b00
	s_waitcnt lgkmcnt(1)
	v_add_f32_e32 v0, v0, v5
	s_waitcnt lgkmcnt(0)
	v_add_f32_e32 v1, v1, v6
	ds_bpermute_b32 v5, v9, v0
	ds_bpermute_b32 v6, v9, v1
	s_waitcnt lgkmcnt(1)
	v_add_f32_e32 v0, v0, v5
	s_waitcnt lgkmcnt(0)
	v_add_f32_e32 v1, v1, v6
	ds_bpermute_b32 v5, v3, v0
	ds_bpermute_b32 v3, v3, v1
	s_waitcnt lgkmcnt(1)
	v_add_f32_e32 v0, v0, v5
	s_waitcnt lgkmcnt(0)
	v_add_f32_e32 v1, v1, v3
	ds_bpermute_b32 v3, v4, v0
	ds_bpermute_b32 v4, v4, v1
	s_waitcnt lgkmcnt(1)
	v_add_f32_e32 v0, v0, v3
	s_waitcnt lgkmcnt(0)
	v_add_f32_e32 v1, v1, v4
	v_mul_f32_e32 v0, 0x3fb8aa3b, v0
	v_mul_f32_e32 v1, 0x3fb8aa3b, v1
	v_exp_f32_e32 v0, v0
	v_exp_f32_e32 v1, v1
	s_nop 0
	v_sub_f32_e32 v0, v0, v1
	v_add_f32_e32 v150, 0x3e4ccccd, v0
	s_mov_b32 s100, 1
	s_branch .LBB0_624

.LBB0_624:
	s_barrier
	s_mov_b64 s[0:1], exec
	v_readlane_b32 s2, v255, 0
	v_readlane_b32 s3, v255, 1
	s_and_b64 s[2:3], s[0:1], s[2:3]
	s_mov_b64 exec, s[2:3]
	s_cbranch_execz .LBB0_628
	s_mov_b64 s[4:5], exec
	v_mbcnt_lo_u32_b32 v0, s4, 0
	v_mbcnt_hi_u32_b32 v0, s5, v0
	v_cmp_eq_u32_e32 vcc, 0, v0
	s_and_saveexec_b64 s[2:3], vcc
	s_cbranch_execz .LBB0_627
	s_cmp_lg_u32 s100, 0
	s_cbranch_scc1 .Lmy_p3_first
	s_bcnt1_i32_b64 s4, s[4:5]
	v_mov_b32_e32 v1, s4
	v_readlane_b32 s4, v255, 49
	v_readlane_b32 s5, v255, 50
	s_nop 4
	global_atomic_add v1, v2, v1, s[4:5] sc0
	s_waitcnt vmcnt(0)
	v_readlane_b32 s4, v255, 47
	s_nop 1
	v_add_u32_e32 v1, s4, v1
	s_branch .LBB0_627
.Lmy_p3_first:
	v_readlane_b32 s4, v255, 46
	s_mov_b32 s100, 0
	s_nop 1
	v_mov_b32_e32 v1, s4
